# flat grid barriers in one stage: every workgroup polls the 256 arrival flags itself, no release word
# baseline (speedup 1.0000x reference)
.LBB0_119:
	s_or_b64 exec, exec, s[6:7]
	s_add_u32 s6, s34, 0x44800
	s_addc_u32 s7, s35, 0
	v_lshlrev_b32_e32 v2, 2, v1
	v_mov_b32_e32 v3, 0
	v_lshl_add_u64 v[4:5], s[22:23], 0, v[2:3]
	s_mov_b32 s0, 1
	s_branch .LBB0_122

.LBB0_137:
	s_branch .LBB0_151
	s_and_saveexec_b64 s[22:23], s[4:5]
	s_cbranch_execz .LBB0_139
	v_mov_b32_e32 v2, 0
	v_mov_b32_e32 v3, 1
	global_store_dword v2, v3, s[6:7] sc1

.LBB0_511:
	s_or_b64 exec, exec, s[6:7]
	s_add_u32 s6, s34, 0x44800
	s_addc_u32 s7, s35, 0
	v_lshlrev_b32_e32 v2, 2, v1
	v_mov_b32_e32 v3, 0
	v_lshl_add_u64 v[4:5], s[8:9], 0, v[2:3]
	s_mov_b32 s0, 1
	s_branch .LBB0_514

.LBB0_529:
	s_branch .LBB0_542
	s_and_saveexec_b64 s[8:9], s[4:5]
	s_cbranch_execz .LBB0_531
	v_mov_b32_e32 v2, 0
	v_mov_b32_e32 v3, 2
	global_store_dword v2, v3, s[6:7] sc1
